# row statistics of a new row block DMA'd into an LDS table during the K loop; the rstd epilogues read them from LDS instead of waiting for global loads
# baseline (speedup 1.0000x reference)
.Llora_n:
	s_add_u32 s10, s78, 0x80
	s_addc_u32 s11, s79, 0
	s_add_u32 s84, s84, 0x100
	s_addc_u32 s85, s85, 0
	s_mov_b32 s78, 0
	v_add_u32_e32 v148, 0x10000, v185
	s_setprio 2
	ds_read_b128 v[128:131], v148 offset:0
	ds_read_b128 v[132:135], v148 offset:1024
	ds_read_b128 v[136:139], v148 offset:2048
	ds_read_b128 v[140:143], v148 offset:3072
	ds_read_b128 v[218:221], v148 offset:16384
	ds_read_b128 v[222:225], v148 offset:17408
	ds_read_b128 v[226:229], v148 offset:18432
	ds_read_b128 v[230:233], v148 offset:19456
	ds_read_b128 v[162:165], v188 offset:0
	ds_read_b128 v[190:193], v188 offset:1024
	ds_read_b128 v[194:197], v188 offset:2048
	ds_read_b128 v[198:201], v188 offset:3072
	ds_read_b128 v[202:205], v188 offset:4096
	ds_read_b128 v[206:209], v188 offset:5120
	ds_read_b128 v[210:213], v188 offset:6144
	ds_read_b128 v[214:217], v188 offset:7168
	s_add_i32 s72, s78, 2
	s_add_u32 s79, s10, 0x80
	s_addc_u32 vcc_lo, s11, 0
	s_cmp_eq_u32 s15, s78
	s_cselect_b32 s78, s12, s84
	s_cselect_b32 vcc_hi, s49, vcc_lo
	s_cselect_b32 vcc_lo, s48, s79
	s_cselect_b32 s79, s13, s85
	s_add_u32 s4, s10, s26
	s_addc_u32 s5, s11, 0
	s_add_i32 m0, s81, 0xc000
	s_nop 0
	global_load_lds_dwordx4 v152, s[4:5]
	s_add_i32 m0, s81, 0xe000
	s_nop 0
	global_load_lds_dwordx4 v144, s[4:5]
	s_add_u32 s10, s10, 0x100
	s_addc_u32 s11, s11, 0
	s_add_u32 s84, s84, 0x100
	s_addc_u32 s85, s85, 0
	s_setprio 0
	s_waitcnt vmcnt(8)
	s_waitcnt lgkmcnt(0)
	s_barrier
	v_mfma_f32_16x16x32_bf16 v[124:127], v[128:131], v[162:165], 0
	v_mfma_f32_16x16x32_bf16 v[116:119], v[136:139], v[162:165], 0
	v_mfma_f32_16x16x32_bf16 v[120:123], v[128:131], v[194:197], 0
	v_mfma_f32_16x16x32_bf16 v[112:115], v[136:139], v[194:197], 0
	v_mfma_f32_16x16x32_bf16 v[92:95], v[128:131], v[202:205], 0
	v_mfma_f32_16x16x32_bf16 v[84:87], v[136:139], v[202:205], 0
	v_mfma_f32_16x16x32_bf16 v[88:91], v[128:131], v[210:213], 0
	v_mfma_f32_16x16x32_bf16 v[80:83], v[136:139], v[210:213], 0
	v_mfma_f32_16x16x32_bf16 v[124:127], v[132:135], v[190:193], v[124:127]
	v_mfma_f32_16x16x32_bf16 v[116:119], v[140:143], v[190:193], v[116:119]
	v_mfma_f32_16x16x32_bf16 v[120:123], v[132:135], v[198:201], v[120:123]
	v_mfma_f32_16x16x32_bf16 v[112:115], v[140:143], v[198:201], v[112:115]
	v_mfma_f32_16x16x32_bf16 v[92:95], v[132:135], v[206:209], v[92:95]
	v_mfma_f32_16x16x32_bf16 v[84:87], v[140:143], v[206:209], v[84:87]
	v_mfma_f32_16x16x32_bf16 v[88:91], v[132:135], v[214:217], v[88:91]
	v_mfma_f32_16x16x32_bf16 v[80:83], v[140:143], v[214:217], v[80:83]
	v_mfma_f32_16x16x32_bf16 v[108:111], v[218:221], v[162:165], 0
	v_mfma_f32_16x16x32_bf16 v[100:103], v[226:229], v[162:165], 0
	v_mfma_f32_16x16x32_bf16 v[104:107], v[218:221], v[194:197], 0
	v_mfma_f32_16x16x32_bf16 v[96:99], v[226:229], v[194:197], 0
	v_mfma_f32_16x16x32_bf16 v[76:79], v[218:221], v[202:205], 0
	v_mfma_f32_16x16x32_bf16 v[68:71], v[226:229], v[202:205], 0
	v_mfma_f32_16x16x32_bf16 v[72:75], v[218:221], v[210:213], 0
	v_mfma_f32_16x16x32_bf16 v[64:67], v[226:229], v[210:213], 0
	v_mfma_f32_16x16x32_bf16 v[108:111], v[222:225], v[190:193], v[108:111]
	v_mfma_f32_16x16x32_bf16 v[100:103], v[230:233], v[190:193], v[100:103]
	v_mfma_f32_16x16x32_bf16 v[104:107], v[222:225], v[198:201], v[104:107]
	v_mfma_f32_16x16x32_bf16 v[96:99], v[230:233], v[198:201], v[96:99]
	v_mfma_f32_16x16x32_bf16 v[76:79], v[222:225], v[206:209], v[76:79]
	v_mfma_f32_16x16x32_bf16 v[68:71], v[230:233], v[206:209], v[68:71]
	v_mfma_f32_16x16x32_bf16 v[72:75], v[222:225], v[214:217], v[72:75]
	v_mfma_f32_16x16x32_bf16 v[64:67], v[230:233], v[214:217], v[64:67]
	s_barrier
	s_bitcmp1_b32 s45, 0
	s_cbranch_scc1 .Lsq_skip
	s_cmp_eq_u32 s98, s20
	s_cbranch_scc1 .Lsq_skip
	v_mbcnt_lo_u32_b32 v166, -1, 0
	v_mbcnt_hi_u32_b32 v166, -1, v166
	v_lshlrev_b32_e32 v166, 4, v166
	v_readfirstlane_b32 s4, v156
	v_readfirstlane_b32 s5, v157
	s_lshl_b32 s99, s20, 14
	s_lshl_b32 s100, s81, 1
	s_add_u32 s99, s99, s100
	s_add_u32 s4, s4, s99
	s_addc_u32 s5, s5, 0
	s_add_i32 s100, s100, 0x20000
	s_cmp_eq_u32 s81, 0x1c00
	s_cselect_b32 s101, 0x800, 0
	s_add_i32 s100, s100, s101
	s_mov_b32 m0, s100
	s_nop 0
	global_load_lds_dwordx4 v166, s[4:5]
	s_add_u32 s4, s4, 0x400
	s_addc_u32 s5, s5, 0
	s_add_i32 m0, s100, 0x400
	s_nop 0
	global_load_lds_dwordx4 v166, s[4:5]
.Lsq_skip:
	s_setprio 2
	ds_read_b128 v[162:165], v188 offset:16384
	ds_read_b128 v[190:193], v188 offset:17408
	ds_read_b128 v[194:197], v188 offset:18432
	ds_read_b128 v[198:201], v188 offset:19456
	ds_read_b128 v[202:205], v188 offset:20480
	ds_read_b128 v[206:209], v188 offset:21504
	ds_read_b128 v[210:213], v188 offset:22528
	ds_read_b128 v[214:217], v188 offset:23552
	s_add_i32 m0, s81, 0x10000
	s_nop 0
	global_load_lds_dwordx4 v154, s[78:79]
	s_add_i32 m0, s81, 0x12000
	s_nop 0
	global_load_lds_dwordx4 v146, s[78:79]
	s_add_i32 m0, s81, 0x0
	s_nop 0
	global_load_lds_dwordx4 v152, vcc
	s_add_i32 m0, s81, 0x2000
	s_nop 0
	global_load_lds_dwordx4 v144, vcc
	s_add_u32 s4, s78, s26
	s_addc_u32 s5, s79, 0
	s_add_i32 m0, s81, 0x14000
	s_nop 0
	global_load_lds_dwordx4 v154, s[4:5]
	s_add_i32 m0, s81, 0x16000
	s_nop 0
	global_load_lds_dwordx4 v146, s[4:5]
	s_setprio 0
	s_waitcnt vmcnt(8)
	s_waitcnt lgkmcnt(0)
	s_barrier
	v_mfma_f32_16x16x32_bf16 v[60:63], v[128:131], v[162:165], 0
	v_mfma_f32_16x16x32_bf16 v[56:59], v[136:139], v[162:165], 0
	v_mfma_f32_16x16x32_bf16 v[52:55], v[128:131], v[194:197], 0
	v_mfma_f32_16x16x32_bf16 v[48:51], v[136:139], v[194:197], 0
	v_mfma_f32_16x16x32_bf16 v[28:31], v[128:131], v[202:205], 0
	v_mfma_f32_16x16x32_bf16 v[20:23], v[136:139], v[202:205], 0
	v_mfma_f32_16x16x32_bf16 v[24:27], v[128:131], v[210:213], 0
	v_mfma_f32_16x16x32_bf16 v[16:19], v[136:139], v[210:213], 0
	v_mfma_f32_16x16x32_bf16 v[60:63], v[132:135], v[190:193], v[60:63]
	v_mfma_f32_16x16x32_bf16 v[56:59], v[140:143], v[190:193], v[56:59]
	v_mfma_f32_16x16x32_bf16 v[52:55], v[132:135], v[198:201], v[52:55]
	v_mfma_f32_16x16x32_bf16 v[48:51], v[140:143], v[198:201], v[48:51]
	v_mfma_f32_16x16x32_bf16 v[28:31], v[132:135], v[206:209], v[28:31]
	v_mfma_f32_16x16x32_bf16 v[20:23], v[140:143], v[206:209], v[20:23]
	v_mfma_f32_16x16x32_bf16 v[24:27], v[132:135], v[214:217], v[24:27]
	v_mfma_f32_16x16x32_bf16 v[16:19], v[140:143], v[214:217], v[16:19]
	v_mfma_f32_16x16x32_bf16 v[44:47], v[218:221], v[162:165], 0
	v_mfma_f32_16x16x32_bf16 v[36:39], v[226:229], v[162:165], 0
	v_mfma_f32_16x16x32_bf16 v[40:43], v[218:221], v[194:197], 0
	v_mfma_f32_16x16x32_bf16 v[32:35], v[226:229], v[194:197], 0
	v_mfma_f32_16x16x32_bf16 v[12:15], v[218:221], v[202:205], 0
	v_mfma_f32_16x16x32_bf16 v[4:7], v[226:229], v[202:205], 0
	v_mfma_f32_16x16x32_bf16 v[8:11], v[218:221], v[210:213], 0
	v_mfma_f32_16x16x32_bf16 v[0:3], v[226:229], v[210:213], 0
	v_mfma_f32_16x16x32_bf16 v[44:47], v[222:225], v[190:193], v[44:47]
	v_mfma_f32_16x16x32_bf16 v[36:39], v[230:233], v[190:193], v[36:39]
	v_mfma_f32_16x16x32_bf16 v[40:43], v[222:225], v[198:201], v[40:43]
	v_mfma_f32_16x16x32_bf16 v[32:35], v[230:233], v[198:201], v[32:35]
	v_mfma_f32_16x16x32_bf16 v[12:15], v[222:225], v[206:209], v[12:15]
	v_mfma_f32_16x16x32_bf16 v[4:7], v[230:233], v[206:209], v[4:7]
	v_mfma_f32_16x16x32_bf16 v[8:11], v[222:225], v[214:217], v[8:11]
	v_mfma_f32_16x16x32_bf16 v[0:3], v[230:233], v[214:217], v[0:3]
	s_barrier
	s_setprio 2
	ds_read_b128 v[128:131], v148 offset:32768
	ds_read_b128 v[132:135], v148 offset:33792
	ds_read_b128 v[136:139], v148 offset:34816
	ds_read_b128 v[140:143], v148 offset:35840
	ds_read_b128 v[218:221], v148 offset:49152
	ds_read_b128 v[222:225], v148 offset:50176
	ds_read_b128 v[226:229], v148 offset:51200
	ds_read_b128 v[230:233], v148 offset:52224
	ds_read_b128 v[162:165], v188 offset:32768
	ds_read_b128 v[190:193], v188 offset:33792
	ds_read_b128 v[194:197], v188 offset:34816
	ds_read_b128 v[198:201], v188 offset:35840
	ds_read_b128 v[202:205], v188 offset:36864
	ds_read_b128 v[206:209], v188 offset:37888
	ds_read_b128 v[210:213], v188 offset:38912
	ds_read_b128 v[214:217], v188 offset:39936
	s_add_u32 s4, vcc_lo, s26
	s_addc_u32 s5, vcc_hi, 0
	s_add_i32 m0, s81, 0x4000
	s_nop 0
	global_load_lds_dwordx4 v152, s[4:5]
	s_add_i32 m0, s81, 0x6000
	s_nop 0
	global_load_lds_dwordx4 v144, s[4:5]
	s_setprio 0
	s_waitcnt vmcnt(8)
	s_waitcnt lgkmcnt(0)
	s_barrier
	v_mfma_f32_16x16x32_bf16 v[124:127], v[128:131], v[162:165], v[124:127]
	v_mfma_f32_16x16x32_bf16 v[116:119], v[136:139], v[162:165], v[116:119]
	v_mfma_f32_16x16x32_bf16 v[120:123], v[128:131], v[194:197], v[120:123]
	v_mfma_f32_16x16x32_bf16 v[112:115], v[136:139], v[194:197], v[112:115]
	v_mfma_f32_16x16x32_bf16 v[92:95], v[128:131], v[202:205], v[92:95]
	v_mfma_f32_16x16x32_bf16 v[84:87], v[136:139], v[202:205], v[84:87]
	v_mfma_f32_16x16x32_bf16 v[88:91], v[128:131], v[210:213], v[88:91]
	v_mfma_f32_16x16x32_bf16 v[80:83], v[136:139], v[210:213], v[80:83]
	v_mfma_f32_16x16x32_bf16 v[124:127], v[132:135], v[190:193], v[124:127]
	v_mfma_f32_16x16x32_bf16 v[116:119], v[140:143], v[190:193], v[116:119]
	v_mfma_f32_16x16x32_bf16 v[120:123], v[132:135], v[198:201], v[120:123]
	v_mfma_f32_16x16x32_bf16 v[112:115], v[140:143], v[198:201], v[112:115]
	v_mfma_f32_16x16x32_bf16 v[92:95], v[132:135], v[206:209], v[92:95]
	v_mfma_f32_16x16x32_bf16 v[84:87], v[140:143], v[206:209], v[84:87]
	v_mfma_f32_16x16x32_bf16 v[88:91], v[132:135], v[214:217], v[88:91]
	v_mfma_f32_16x16x32_bf16 v[80:83], v[140:143], v[214:217], v[80:83]
	v_mfma_f32_16x16x32_bf16 v[108:111], v[218:221], v[162:165], v[108:111]
	v_mfma_f32_16x16x32_bf16 v[100:103], v[226:229], v[162:165], v[100:103]
	v_mfma_f32_16x16x32_bf16 v[104:107], v[218:221], v[194:197], v[104:107]
	v_mfma_f32_16x16x32_bf16 v[96:99], v[226:229], v[194:197], v[96:99]
	v_mfma_f32_16x16x32_bf16 v[76:79], v[218:221], v[202:205], v[76:79]
	v_mfma_f32_16x16x32_bf16 v[68:71], v[226:229], v[202:205], v[68:71]
	v_mfma_f32_16x16x32_bf16 v[72:75], v[218:221], v[210:213], v[72:75]
	v_mfma_f32_16x16x32_bf16 v[64:67], v[226:229], v[210:213], v[64:67]
	v_mfma_f32_16x16x32_bf16 v[108:111], v[222:225], v[190:193], v[108:111]
	v_mfma_f32_16x16x32_bf16 v[100:103], v[230:233], v[190:193], v[100:103]
	v_mfma_f32_16x16x32_bf16 v[104:107], v[222:225], v[198:201], v[104:107]
	v_mfma_f32_16x16x32_bf16 v[96:99], v[230:233], v[198:201], v[96:99]
	v_mfma_f32_16x16x32_bf16 v[76:79], v[222:225], v[206:209], v[76:79]
	v_mfma_f32_16x16x32_bf16 v[68:71], v[230:233], v[206:209], v[68:71]
	v_mfma_f32_16x16x32_bf16 v[72:75], v[222:225], v[214:217], v[72:75]
	v_mfma_f32_16x16x32_bf16 v[64:67], v[230:233], v[214:217], v[64:67]
	s_barrier
	s_setprio 2
	ds_read_b128 v[162:165], v188 offset:49152
	ds_read_b128 v[190:193], v188 offset:50176
	ds_read_b128 v[194:197], v188 offset:51200
	ds_read_b128 v[198:201], v188 offset:52224
	ds_read_b128 v[202:205], v188 offset:53248
	ds_read_b128 v[206:209], v188 offset:54272
	ds_read_b128 v[210:213], v188 offset:55296
	ds_read_b128 v[214:217], v188 offset:56320
	s_add_u32 s4, s78, 0x80
	s_addc_u32 s5, s79, 0
	s_add_i32 m0, s81, 0x18000
	s_nop 0
	global_load_lds_dwordx4 v154, s[4:5]
	s_add_i32 m0, s81, 0x1a000
	s_nop 0
	global_load_lds_dwordx4 v146, s[4:5]
	s_add_u32 s4, vcc_lo, 0x80
	s_addc_u32 s5, vcc_hi, 0
	s_add_i32 m0, s81, 0x8000
	s_nop 0
	global_load_lds_dwordx4 v152, s[4:5]
	s_add_i32 m0, s81, 0xa000
	s_nop 0
	global_load_lds_dwordx4 v144, s[4:5]
	s_add_u32 s4, s78, s26
	s_addc_u32 s5, s79, 0
	s_add_u32 s4, s4, 0x80
	s_addc_u32 s5, s5, 0
	s_add_i32 m0, s81, 0x1c000
	s_nop 0
	global_load_lds_dwordx4 v154, s[4:5]
	s_add_i32 m0, s81, 0x1e000
	s_nop 0
	global_load_lds_dwordx4 v146, s[4:5]
	s_setprio 0
	s_waitcnt vmcnt(8)
	s_waitcnt lgkmcnt(0)
	s_barrier
	v_mfma_f32_16x16x32_bf16 v[60:63], v[128:131], v[162:165], v[60:63]
	v_mfma_f32_16x16x32_bf16 v[56:59], v[136:139], v[162:165], v[56:59]
	v_mfma_f32_16x16x32_bf16 v[52:55], v[128:131], v[194:197], v[52:55]
	v_mfma_f32_16x16x32_bf16 v[48:51], v[136:139], v[194:197], v[48:51]
	v_mfma_f32_16x16x32_bf16 v[28:31], v[128:131], v[202:205], v[28:31]
	v_mfma_f32_16x16x32_bf16 v[20:23], v[136:139], v[202:205], v[20:23]
	v_mfma_f32_16x16x32_bf16 v[24:27], v[128:131], v[210:213], v[24:27]
	v_mfma_f32_16x16x32_bf16 v[16:19], v[136:139], v[210:213], v[16:19]
	v_mfma_f32_16x16x32_bf16 v[60:63], v[132:135], v[190:193], v[60:63]
	v_mfma_f32_16x16x32_bf16 v[56:59], v[140:143], v[190:193], v[56:59]
	v_mfma_f32_16x16x32_bf16 v[52:55], v[132:135], v[198:201], v[52:55]
	v_mfma_f32_16x16x32_bf16 v[48:51], v[140:143], v[198:201], v[48:51]
	v_mfma_f32_16x16x32_bf16 v[28:31], v[132:135], v[206:209], v[28:31]
	v_mfma_f32_16x16x32_bf16 v[20:23], v[140:143], v[206:209], v[20:23]
	v_mfma_f32_16x16x32_bf16 v[24:27], v[132:135], v[214:217], v[24:27]
	v_mfma_f32_16x16x32_bf16 v[16:19], v[140:143], v[214:217], v[16:19]
	v_mfma_f32_16x16x32_bf16 v[44:47], v[218:221], v[162:165], v[44:47]
	v_mfma_f32_16x16x32_bf16 v[36:39], v[226:229], v[162:165], v[36:39]
	v_mfma_f32_16x16x32_bf16 v[40:43], v[218:221], v[194:197], v[40:43]
	v_mfma_f32_16x16x32_bf16 v[32:35], v[226:229], v[194:197], v[32:35]
	v_mfma_f32_16x16x32_bf16 v[12:15], v[218:221], v[202:205], v[12:15]
	v_mfma_f32_16x16x32_bf16 v[4:7], v[226:229], v[202:205], v[4:7]
	v_mfma_f32_16x16x32_bf16 v[8:11], v[218:221], v[210:213], v[8:11]
	v_mfma_f32_16x16x32_bf16 v[0:3], v[226:229], v[210:213], v[0:3]
	v_mfma_f32_16x16x32_bf16 v[44:47], v[222:225], v[190:193], v[44:47]
	v_mfma_f32_16x16x32_bf16 v[36:39], v[230:233], v[190:193], v[36:39]
	v_mfma_f32_16x16x32_bf16 v[40:43], v[222:225], v[198:201], v[40:43]
	v_mfma_f32_16x16x32_bf16 v[32:35], v[230:233], v[198:201], v[32:35]
	v_mfma_f32_16x16x32_bf16 v[12:15], v[222:225], v[206:209], v[12:15]
	v_mfma_f32_16x16x32_bf16 v[4:7], v[230:233], v[206:209], v[4:7]
	v_mfma_f32_16x16x32_bf16 v[8:11], v[222:225], v[214:217], v[8:11]
	v_mfma_f32_16x16x32_bf16 v[0:3], v[230:233], v[214:217], v[0:3]
	s_cmp_ge_u32 s72, s76
	s_mov_b32 s78, s72
	s_barrier
	s_cbranch_scc1 .Lkloop_done
	.p2align 6

.LBB0_534:
	s_andn2_b64 vcc, exec, s[10:11]
	s_cbranch_vccnz .LBB0_536
	v_ashrrev_i32_e32 v163, 31, v162
	s_cmp_eq_u32 s98, s20
	s_cbranch_scc1 .Lep2_fast
	s_mov_b32 s98, s20
	v_and_b32_e32 v164, 12, v187
	v_lshlrev_b32_e32 v164, 2, v164
	v_lshl_add_u32 v164, v151, 6, v164
	v_add_u32_e32 v164, 0x20000, v164
	s_cmp_ge_u32 s81, 0x1000
	s_cselect_b32 s10, 0x800, 0
	v_add_u32_e32 v165, s10, v164
	ds_read_b128 v[190:193], v164
	ds_read_b128 v[194:197], v164 offset:1024
	ds_read_b128 v[198:201], v164 offset:2048
	ds_read_b128 v[202:205], v164 offset:3072
	ds_read_b128 v[206:209], v164 offset:8192
	ds_read_b128 v[210:213], v164 offset:9216
	ds_read_b128 v[214:217], v165 offset:10240
	ds_read_b128 v[218:221], v165 offset:11264
	v_mov_b32_e32 v173, s56
	s_waitcnt lgkmcnt(0)
	v_add_f32_e32 v190, v190, v191
	v_add_f32_e32 v194, v194, v195
	v_add_f32_e32 v198, v198, v199
	v_add_f32_e32 v202, v202, v203
	v_add_f32_e32 v206, v206, v207
	v_add_f32_e32 v210, v210, v211
	v_add_f32_e32 v214, v214, v215
	v_add_f32_e32 v218, v218, v219
	v_add_f32_e32 v192, v192, v193
	v_add_f32_e32 v196, v196, v197
	v_add_f32_e32 v200, v200, v201
	v_add_f32_e32 v204, v204, v205
	v_add_f32_e32 v208, v208, v209
	v_add_f32_e32 v212, v212, v213
	v_add_f32_e32 v216, v216, v217
	v_add_f32_e32 v220, v220, v221
	v_add_f32_e32 v242, v190, v192
	v_add_f32_e32 v243, v194, v196
	v_add_f32_e32 v244, v198, v200
	v_add_f32_e32 v245, v202, v204
	v_add_f32_e32 v246, v206, v208
	v_add_f32_e32 v247, v210, v212
	v_add_f32_e32 v248, v214, v216
	v_add_f32_e32 v249, v218, v220
	v_mov_b32_e32 v135, v242
	v_mov_b32_e32 v136, v243
	v_mov_b32_e32 v137, v244
	v_mov_b32_e32 v138, v245
	v_mov_b32_e32 v139, v246
	v_mov_b32_e32 v140, v247
	v_mov_b32_e32 v141, v248
	v_mov_b32_e32 v142, v249
	s_nop 1
	v_permlane16_swap_b32_e32 v242, v135
	v_permlane16_swap_b32_e32 v243, v136
	v_permlane16_swap_b32_e32 v244, v137
	v_permlane16_swap_b32_e32 v245, v138
	v_permlane16_swap_b32_e32 v246, v139
	v_permlane16_swap_b32_e32 v247, v140
	v_permlane16_swap_b32_e32 v248, v141
	v_permlane16_swap_b32_e32 v249, v142
	v_add_f32_e32 v242, v242, v135
	v_add_f32_e32 v243, v243, v136
	v_add_f32_e32 v244, v244, v137
	v_add_f32_e32 v245, v245, v138
	v_add_f32_e32 v246, v246, v139
	v_add_f32_e32 v247, v247, v140
	v_add_f32_e32 v248, v248, v141
	v_add_f32_e32 v249, v249, v142
	v_mov_b32_e32 v135, v242
	v_mov_b32_e32 v136, v243
	v_mov_b32_e32 v137, v244
	v_mov_b32_e32 v138, v245
	v_mov_b32_e32 v139, v246
	v_mov_b32_e32 v140, v247
	v_mov_b32_e32 v141, v248
	v_mov_b32_e32 v142, v249
	s_nop 1
	v_permlane32_swap_b32_e32 v242, v135
	v_permlane32_swap_b32_e32 v243, v136
	v_permlane32_swap_b32_e32 v244, v137
	v_permlane32_swap_b32_e32 v245, v138
	v_permlane32_swap_b32_e32 v246, v139
	v_permlane32_swap_b32_e32 v247, v140
	v_permlane32_swap_b32_e32 v248, v141
	v_permlane32_swap_b32_e32 v249, v142
	v_add_f32_e32 v242, v242, v135
	v_add_f32_e32 v243, v243, v136
	v_add_f32_e32 v244, v244, v137
	v_add_f32_e32 v245, v245, v138
	v_add_f32_e32 v246, v246, v139
	v_add_f32_e32 v247, v247, v140
	v_add_f32_e32 v248, v248, v141
	v_add_f32_e32 v249, v249, v142
	v_fma_f32 v242, v242, s54, v173
	v_fma_f32 v243, v243, s54, v173
	v_fma_f32 v244, v244, s54, v173
	v_fma_f32 v245, v245, s54, v173
	v_fma_f32 v246, v246, s54, v173
	v_fma_f32 v247, v247, s54, v173
	v_fma_f32 v248, v248, s54, v173
	v_fma_f32 v249, v249, s54, v173
	v_rsq_f32_e32 v250, v242
	v_rsq_f32_e32 v251, v243
	v_rsq_f32_e32 v252, v244
	v_rsq_f32_e32 v253, v245
	v_rsq_f32_e32 v168, v246
	v_rsq_f32_e32 v170, v247
	v_rsq_f32_e32 v176, v248
	v_rsq_f32_e32 v178, v249
	s_nop 0

.LBB0_537:
	s_andn2_b64 vcc, exec, s[10:11]
	s_cbranch_vccnz .LBB0_514
	s_mov_b64 s[10:11], -1
	s_cmp_eq_u32 s45, 1
	v_ashrrev_i32_e32 v163, 31, v162
	v_or_b32_e32 v134, 16, v162
	v_or_b32_e32 v130, 32, v162
	v_or_b32_e32 v132, 48, v162
	v_add_u32_e32 v128, 0x80, v162
	s_cbranch_scc1 .LBB0_540
	s_cmp_eq_u32 s98, s20
	s_cbranch_scc1 .Lep0_fast
	s_mov_b32 s98, s20
	v_and_b32_e32 v164, 12, v187
	v_lshlrev_b32_e32 v164, 2, v164
	v_lshl_add_u32 v164, v151, 6, v164
	v_add_u32_e32 v164, 0x20000, v164
	s_cmp_ge_u32 s81, 0x1000
	s_cselect_b32 s10, 0x800, 0
	v_add_u32_e32 v165, s10, v164
	ds_read_b128 v[190:193], v164
	ds_read_b128 v[194:197], v164 offset:1024
	ds_read_b128 v[198:201], v164 offset:2048
	ds_read_b128 v[202:205], v164 offset:3072
	ds_read_b128 v[206:209], v164 offset:8192
	ds_read_b128 v[210:213], v164 offset:9216
	ds_read_b128 v[214:217], v165 offset:10240
	ds_read_b128 v[218:221], v165 offset:11264
	v_mov_b32_e32 v173, s56
	s_waitcnt lgkmcnt(0)
	v_add_f32_e32 v190, v190, v191
	v_add_f32_e32 v194, v194, v195
	v_add_f32_e32 v198, v198, v199
	v_add_f32_e32 v202, v202, v203
	v_add_f32_e32 v206, v206, v207
	v_add_f32_e32 v210, v210, v211
	v_add_f32_e32 v214, v214, v215
	v_add_f32_e32 v218, v218, v219
	v_add_f32_e32 v192, v192, v193
	v_add_f32_e32 v196, v196, v197
	v_add_f32_e32 v200, v200, v201
	v_add_f32_e32 v204, v204, v205
	v_add_f32_e32 v208, v208, v209
	v_add_f32_e32 v212, v212, v213
	v_add_f32_e32 v216, v216, v217
	v_add_f32_e32 v220, v220, v221
	v_add_f32_e32 v242, v190, v192
	v_add_f32_e32 v243, v194, v196
	v_add_f32_e32 v244, v198, v200
	v_add_f32_e32 v245, v202, v204
	v_add_f32_e32 v246, v206, v208
	v_add_f32_e32 v247, v210, v212
	v_add_f32_e32 v248, v214, v216
	v_add_f32_e32 v249, v218, v220
	v_mov_b32_e32 v135, v242
	v_mov_b32_e32 v136, v243
	v_mov_b32_e32 v137, v244
	v_mov_b32_e32 v138, v245
	v_mov_b32_e32 v139, v246
	v_mov_b32_e32 v140, v247
	v_mov_b32_e32 v141, v248
	v_mov_b32_e32 v142, v249
	s_nop 1
	v_permlane16_swap_b32_e32 v242, v135
	v_permlane16_swap_b32_e32 v243, v136
	v_permlane16_swap_b32_e32 v244, v137
	v_permlane16_swap_b32_e32 v245, v138
	v_permlane16_swap_b32_e32 v246, v139
	v_permlane16_swap_b32_e32 v247, v140
	v_permlane16_swap_b32_e32 v248, v141
	v_permlane16_swap_b32_e32 v249, v142
	v_add_f32_e32 v242, v242, v135
	v_add_f32_e32 v243, v243, v136
	v_add_f32_e32 v244, v244, v137
	v_add_f32_e32 v245, v245, v138
	v_add_f32_e32 v246, v246, v139
	v_add_f32_e32 v247, v247, v140
	v_add_f32_e32 v248, v248, v141
	v_add_f32_e32 v249, v249, v142
	v_mov_b32_e32 v135, v242
	v_mov_b32_e32 v136, v243
	v_mov_b32_e32 v137, v244
	v_mov_b32_e32 v138, v245
	v_mov_b32_e32 v139, v246
	v_mov_b32_e32 v140, v247
	v_mov_b32_e32 v141, v248
	v_mov_b32_e32 v142, v249
	s_nop 1
	v_permlane32_swap_b32_e32 v242, v135
	v_permlane32_swap_b32_e32 v243, v136
	v_permlane32_swap_b32_e32 v244, v137
	v_permlane32_swap_b32_e32 v245, v138
	v_permlane32_swap_b32_e32 v246, v139
	v_permlane32_swap_b32_e32 v247, v140
	v_permlane32_swap_b32_e32 v248, v141
	v_permlane32_swap_b32_e32 v249, v142
	v_add_f32_e32 v242, v242, v135
	v_add_f32_e32 v243, v243, v136
	v_add_f32_e32 v244, v244, v137
	v_add_f32_e32 v245, v245, v138
	v_add_f32_e32 v246, v246, v139
	v_add_f32_e32 v247, v247, v140
	v_add_f32_e32 v248, v248, v141
	v_add_f32_e32 v249, v249, v142
	v_fma_f32 v242, v242, s54, v173
	v_fma_f32 v243, v243, s54, v173
	v_fma_f32 v244, v244, s54, v173
	v_fma_f32 v245, v245, s54, v173
	v_fma_f32 v246, v246, s54, v173
	v_fma_f32 v247, v247, s54, v173
	v_fma_f32 v248, v248, s54, v173
	v_fma_f32 v249, v249, s54, v173
	v_rsq_f32_e32 v250, v242
	v_rsq_f32_e32 v251, v243
	v_rsq_f32_e32 v252, v244
	v_rsq_f32_e32 v253, v245
	v_rsq_f32_e32 v168, v246
	v_rsq_f32_e32 v170, v247
	v_rsq_f32_e32 v176, v248
	v_rsq_f32_e32 v178, v249
	s_nop 0
	v_mul_f32_e32 v250, 0xbfb8aa3b, v250
	v_mul_f32_e32 v251, 0xbfb8aa3b, v251
	v_mul_f32_e32 v252, 0xbfb8aa3b, v252
	v_mul_f32_e32 v253, 0xbfb8aa3b, v253
	v_mul_f32_e32 v168, 0xbfb8aa3b, v168
	v_mul_f32_e32 v170, 0xbfb8aa3b, v170
	v_mul_f32_e32 v176, 0xbfb8aa3b, v176
	v_mul_f32_e32 v178, 0xbfb8aa3b, v178
